# DeltaNet scan rewritten by hand: two value-slices per block share the operand stream (256 active blocks), 3-deep register prefetch
# speedup vs baseline: 1.0243x; 1.0243x over previous
.LBB0_302:
	s_cmp_lt_u32 s96, 256
	s_cbranch_scc0 .LBB0_308
	v_and_b32_e32 v251, 63, v208
	v_lshrrev_b32_e32 v252, 6, v208
	v_and_b32_e32 v253, 15, v251
	v_lshrrev_b32_e32 v251, 4, v251
	v_lshl_add_u32 v250, v252, 4, v253
	v_lshlrev_b32_e32 v209, 4, v251
	v_mul_u32_u24_e32 v247, 272, v253
	v_add_u32_e32 v209, v209, v247
	v_lshlrev_b32_e32 v210, 1, v250
	v_mul_u32_u24_e32 v247, 576, v251
	v_add_u32_e32 v210, v210, v247
	v_add_u32_e32 v210, 4352, v210
	v_lshlrev_b32_e32 v211, 4, v251
	v_mul_u32_u24_e32 v247, 144, v253
	v_add_u32_e32 v211, v211, v247
	v_add_u32_e32 v211, 4352, v211
	v_lshl_add_u32 v212, v252, 5, v253
	v_lshlrev_b32_e32 v212, 1, v212
	v_mul_u32_u24_e32 v247, 1088, v251
	v_add_u32_e32 v212, v212, v247
	v_lshlrev_b32_e32 v213, 4, v251
	v_lshl_add_u32 v213, v250, 8, v213
	v_lshlrev_b32_e32 v214, 4, v251
	v_lshl_add_u32 v214, v250, 7, v214
	v_lshl_add_u32 v215, v252, 5, v253
	v_lshlrev_b32_e32 v215, 7, v215
	v_lshl_add_u32 v215, v251, 4, v215
	v_lshlrev_b32_e32 v248, 3, v251
	v_lshl_add_u32 v248, v250, 8, v248
	v_lshlrev_b32_e32 v249, 3, v251
	v_lshl_add_u32 v249, v250, 11, v249
	s_and_b32 s0, s96, 7
	s_lshr_b32 s23, s96, 5
	s_lshl_b32 s23, s23, 3
	s_add_i32 s0, s0, s23
	s_lshr_b32 s23, s96, 3
	s_and_b32 s23, s23, 3
	s_lshl_b32 s23, s23, 6
	s_lshl_b32 s24, s0, 20
	s_add_u32 s8, s92, s24
	s_addc_u32 s9, s93, 0
	s_add_u32 s10, s8, 0x26000000
	s_addc_u32 s11, s9, 0
	s_add_u32 s12, s8, 0x2a000000
	s_addc_u32 s13, s9, 0
	s_add_u32 s16, s8, 0x1e000000
	s_addc_u32 s17, s9, 0
	s_add_u32 s16, s16, s23
	s_addc_u32 s17, s17, 0
	s_add_u32 s8, s8, 0x22000000
	s_addc_u32 s9, s9, 0
	s_lshl_b32 s24, s0, 19
	s_add_u32 s14, s92, s24
	s_addc_u32 s15, s93, 0
	s_add_u32 s14, s14, 0x2e000000
	s_addc_u32 s15, s15, 0
	s_lshl_b32 s24, s0, 8
	s_add_u32 s18, s92, s24
	s_addc_u32 s19, s93, 0
	s_add_u32 s18, s18, 0x36f00000
	s_addc_u32 s19, s19, 0
	s_lshr_b32 s24, s0, 2
	s_lshl_b32 s24, s24, 23
	s_and_b32 s25, s0, 3
	s_lshl_b32 s25, s25, 8
	s_add_i32 s24, s24, s25
	s_add_i32 s24, s24, s23
	s_add_i32 s24, s24, 1024
	s_add_u32 s20, s92, s24
	s_addc_u32 s21, s93, 0
	v_mov_b32_e32 v250, 0
	v_mov_b32_e32 v240, 0
	v_mov_b32_e32 v241, 0
	v_mov_b32_e32 v242, 0
	v_mov_b32_e32 v243, 0
	v_lshlrev_b32_e32 v251, 4, v208
	ds_write_b128 v251, v[240:243] offset:0
	ds_write_b128 v251, v[240:243] offset:4096
	ds_write_b128 v251, v[240:243] offset:8192
	ds_write_b128 v251, v[240:243] offset:12288
	v_mov_b32_e32 v192, 0
	v_mov_b32_e32 v193, 0
	v_mov_b32_e32 v194, 0
	v_mov_b32_e32 v195, 0
	v_mov_b32_e32 v196, 0
	v_mov_b32_e32 v197, 0
	v_mov_b32_e32 v198, 0
	v_mov_b32_e32 v199, 0
	v_mov_b32_e32 v200, 0
	v_mov_b32_e32 v201, 0
	v_mov_b32_e32 v202, 0
	v_mov_b32_e32 v203, 0
	v_mov_b32_e32 v204, 0
	v_mov_b32_e32 v205, 0
	v_mov_b32_e32 v206, 0
	v_mov_b32_e32 v207, 0
	s_mov_b32 s22, 0
	global_load_dwordx4 v[0:3], v213, s[8:9] offset:0
	global_load_dwordx4 v[4:7], v213, s[8:9] offset:64
	global_load_dwordx4 v[8:11], v213, s[8:9] offset:128
	global_load_dwordx4 v[12:15], v213, s[8:9] offset:192
	global_load_dwordx4 v[16:19], v213, s[10:11] offset:0
	global_load_dwordx4 v[20:23], v213, s[10:11] offset:64
	global_load_dwordx4 v[24:27], v213, s[10:11] offset:128
	global_load_dwordx4 v[28:31], v213, s[10:11] offset:192
	global_load_dwordx4 v[32:35], v214, s[14:15] offset:0
	global_load_dwordx4 v[36:39], v214, s[14:15] offset:64
	global_load_dwordx4 v[40:43], v215, s[12:13] offset:0
	global_load_dwordx4 v[44:47], v215, s[12:13] offset:64
	global_load_dwordx4 v[48:51], v215, s[12:13] offset:2048
	global_load_dwordx4 v[52:55], v215, s[12:13] offset:2112
	global_load_dwordx2 v[56:57], v248, s[16:17] offset:0
	global_load_dwordx2 v[58:59], v248, s[16:17] offset:32
	global_load_dword v62, v250, s[18:19]
	s_cmp_lt_u32 s22, 63
	s_cselect_b32 s0, 0x4000, 0
	s_cselect_b32 s23, 0x2000, 0
	s_cselect_b32 s24, 4, 0
	s_add_u32 s8, s8, s0
	s_addc_u32 s9, s9, 0
	s_add_u32 s10, s10, s0
	s_addc_u32 s11, s11, 0
	s_add_u32 s12, s12, s0
	s_addc_u32 s13, s13, 0
	s_add_u32 s16, s16, s0
	s_addc_u32 s17, s17, 0
	s_add_u32 s14, s14, s23
	s_addc_u32 s15, s15, 0
	s_add_u32 s18, s18, s24
	s_addc_u32 s19, s19, 0
	s_add_i32 s22, s22, 1
	global_load_dwordx4 v[64:67], v213, s[8:9] offset:0
	global_load_dwordx4 v[68:71], v213, s[8:9] offset:64
	global_load_dwordx4 v[72:75], v213, s[8:9] offset:128
	global_load_dwordx4 v[76:79], v213, s[8:9] offset:192
	global_load_dwordx4 v[80:83], v213, s[10:11] offset:0
	global_load_dwordx4 v[84:87], v213, s[10:11] offset:64
	global_load_dwordx4 v[88:91], v213, s[10:11] offset:128
	global_load_dwordx4 v[92:95], v213, s[10:11] offset:192
	global_load_dwordx4 v[96:99], v214, s[14:15] offset:0
	global_load_dwordx4 v[100:103], v214, s[14:15] offset:64
	global_load_dwordx4 v[104:107], v215, s[12:13] offset:0
	global_load_dwordx4 v[108:111], v215, s[12:13] offset:64
	global_load_dwordx4 v[112:115], v215, s[12:13] offset:2048
	global_load_dwordx4 v[116:119], v215, s[12:13] offset:2112
	global_load_dwordx2 v[120:121], v248, s[16:17] offset:0
	global_load_dwordx2 v[122:123], v248, s[16:17] offset:32
	global_load_dword v126, v250, s[18:19]
	s_cmp_lt_u32 s22, 63
	s_cselect_b32 s0, 0x4000, 0
	s_cselect_b32 s23, 0x2000, 0
	s_cselect_b32 s24, 4, 0
	s_add_u32 s8, s8, s0
	s_addc_u32 s9, s9, 0
	s_add_u32 s10, s10, s0
	s_addc_u32 s11, s11, 0
	s_add_u32 s12, s12, s0
	s_addc_u32 s13, s13, 0
	s_add_u32 s16, s16, s0
	s_addc_u32 s17, s17, 0
	s_add_u32 s14, s14, s23
	s_addc_u32 s15, s15, 0
	s_add_u32 s18, s18, s24
	s_addc_u32 s19, s19, 0
	s_add_i32 s22, s22, 1
	s_mov_b32 s26, 0
	s_waitcnt lgkmcnt(0)
	s_barrier
.Lsc_loop:
	global_load_dwordx4 v[128:131], v213, s[8:9] offset:0
	global_load_dwordx4 v[132:135], v213, s[8:9] offset:64
	global_load_dwordx4 v[136:139], v213, s[8:9] offset:128
	global_load_dwordx4 v[140:143], v213, s[8:9] offset:192
	global_load_dwordx4 v[144:147], v213, s[10:11] offset:0
	global_load_dwordx4 v[148:151], v213, s[10:11] offset:64
	global_load_dwordx4 v[152:155], v213, s[10:11] offset:128
	global_load_dwordx4 v[156:159], v213, s[10:11] offset:192
	global_load_dwordx4 v[160:163], v214, s[14:15] offset:0
	global_load_dwordx4 v[164:167], v214, s[14:15] offset:64
	global_load_dwordx4 v[168:171], v215, s[12:13] offset:0
	global_load_dwordx4 v[172:175], v215, s[12:13] offset:64
	global_load_dwordx4 v[176:179], v215, s[12:13] offset:2048
	global_load_dwordx4 v[180:183], v215, s[12:13] offset:2112
	global_load_dwordx2 v[184:185], v248, s[16:17] offset:0
	global_load_dwordx2 v[186:187], v248, s[16:17] offset:32
	global_load_dword v190, v250, s[18:19]
	s_cmp_lt_u32 s22, 63
	s_cselect_b32 s0, 0x4000, 0
	s_cselect_b32 s23, 0x2000, 0
	s_cselect_b32 s24, 4, 0
	s_add_u32 s8, s8, s0
	s_addc_u32 s9, s9, 0
	s_add_u32 s10, s10, s0
	s_addc_u32 s11, s11, 0
	s_add_u32 s12, s12, s0
	s_addc_u32 s13, s13, 0
	s_add_u32 s16, s16, s0
	s_addc_u32 s17, s17, 0
	s_add_u32 s14, s14, s23
	s_addc_u32 s15, s15, 0
	s_add_u32 s18, s18, s24
	s_addc_u32 s19, s19, 0
	s_add_i32 s22, s22, 1
	s_waitcnt vmcnt(34)
	ds_read_b128 v[216:219], v209 offset:0
	ds_read_b128 v[220:223], v209 offset:64
	ds_read_b128 v[224:227], v209 offset:128
	ds_read_b128 v[228:231], v209 offset:192
	s_waitcnt lgkmcnt(0)
	v_mfma_f32_16x16x32_bf16 v[232:235], v[216:219], v[0:3], 0
	v_mfma_f32_16x16x32_bf16 v[236:239], v[216:219], v[16:19], 0
	v_mfma_f32_16x16x32_bf16 v[232:235], v[220:223], v[4:7], v[232:235]
	v_mfma_f32_16x16x32_bf16 v[236:239], v[220:223], v[20:23], v[236:239]
	v_mfma_f32_16x16x32_bf16 v[232:235], v[224:227], v[8:11], v[232:235]
	v_mfma_f32_16x16x32_bf16 v[236:239], v[224:227], v[24:27], v[236:239]
	v_mfma_f32_16x16x32_bf16 v[232:235], v[228:231], v[12:15], v[232:235]
	v_mfma_f32_16x16x32_bf16 v[236:239], v[228:231], v[28:31], v[236:239]
	s_nop 7
	s_nop 1
	v_lshlrev_b32_e32 v244, 16, v56
	v_and_b32_e32 v245, 0xffff0000, v56
	v_lshlrev_b32_e32 v246, 16, v57
	v_and_b32_e32 v247, 0xffff0000, v57
	v_sub_f32_e32 v244, v244, v232
	v_sub_f32_e32 v245, v245, v233
	v_sub_f32_e32 v246, v246, v234
	v_sub_f32_e32 v247, v247, v235
	v_cvt_pk_bf16_f32 v244, v244, v245
	v_cvt_pk_bf16_f32 v246, v246, v247
	ds_write_b16 v210, v244 offset:0
	ds_write_b16_d16_hi v210, v244 offset:144
	ds_write_b16 v210, v246 offset:288
	ds_write_b16_d16_hi v210, v246 offset:432
	ds_read_b128 v[216:219], v209 offset:6656
	ds_read_b128 v[220:223], v209 offset:6720
	ds_read_b128 v[224:227], v209 offset:6784
	ds_read_b128 v[228:231], v209 offset:6848
	s_waitcnt lgkmcnt(0)
	v_mfma_f32_16x16x32_bf16 v[232:235], v[216:219], v[0:3], 0
	v_mfma_f32_16x16x32_bf16 v[240:243], v[216:219], v[16:19], 0
	v_mfma_f32_16x16x32_bf16 v[232:235], v[220:223], v[4:7], v[232:235]
	v_mfma_f32_16x16x32_bf16 v[240:243], v[220:223], v[20:23], v[240:243]
	v_mfma_f32_16x16x32_bf16 v[232:235], v[224:227], v[8:11], v[232:235]
	v_mfma_f32_16x16x32_bf16 v[240:243], v[224:227], v[24:27], v[240:243]
	v_mfma_f32_16x16x32_bf16 v[232:235], v[228:231], v[12:15], v[232:235]
	v_mfma_f32_16x16x32_bf16 v[240:243], v[228:231], v[28:31], v[240:243]
	s_nop 7
	s_nop 1
	v_lshlrev_b32_e32 v244, 16, v58
	v_and_b32_e32 v245, 0xffff0000, v58
	v_lshlrev_b32_e32 v246, 16, v59
	v_and_b32_e32 v247, 0xffff0000, v59
	v_sub_f32_e32 v244, v244, v232
	v_sub_f32_e32 v245, v245, v233
	v_sub_f32_e32 v246, v246, v234
	v_sub_f32_e32 v247, v247, v235
	v_cvt_pk_bf16_f32 v244, v244, v245
	v_cvt_pk_bf16_f32 v246, v246, v247
	ds_write_b16 v210, v244 offset:6656
	ds_write_b16_d16_hi v210, v244 offset:6800
	ds_write_b16 v210, v246 offset:6944
	ds_write_b16_d16_hi v210, v246 offset:7088
	s_waitcnt lgkmcnt(0)
	s_barrier
	ds_read_b128 v[216:219], v211 offset:0
	ds_read_b128 v[220:223], v211 offset:64
	v_mul_f32_e32 v192, v62, v192
	v_mul_f32_e32 v193, v62, v193
	v_mul_f32_e32 v194, v62, v194
	v_mul_f32_e32 v195, v62, v195
	v_mul_f32_e32 v196, v62, v196
	v_mul_f32_e32 v197, v62, v197
	v_mul_f32_e32 v198, v62, v198
	v_mul_f32_e32 v199, v62, v199
	s_waitcnt lgkmcnt(0)
	v_mfma_f32_16x16x32_bf16 v[236:239], v[216:219], v[32:35], v[236:239]
	v_mfma_f32_16x16x32_bf16 v[192:195], v[216:219], v[40:43], v[192:195]
	v_mfma_f32_16x16x32_bf16 v[196:199], v[216:219], v[48:51], v[196:199]
	v_mfma_f32_16x16x32_bf16 v[236:239], v[220:223], v[36:39], v[236:239]
	v_mfma_f32_16x16x32_bf16 v[192:195], v[220:223], v[44:47], v[192:195]
	v_mfma_f32_16x16x32_bf16 v[196:199], v[220:223], v[52:55], v[196:199]
	s_nop 7
	s_nop 1
	v_cvt_pk_bf16_f32 v244, v236, v237
	v_cvt_pk_bf16_f32 v245, v238, v239
	global_store_dwordx2 v249, v[244:245], s[20:21] offset:0
	v_cvt_pk_bf16_f32 v246, v192, v193
	v_cvt_pk_bf16_f32 v247, v194, v195
	ds_write_b16 v212, v246 offset:0
	ds_write_b16_d16_hi v212, v246 offset:272
	ds_write_b16 v212, v247 offset:544
	ds_write_b16_d16_hi v212, v247 offset:816
	v_cvt_pk_bf16_f32 v246, v196, v197
	v_cvt_pk_bf16_f32 v247, v198, v199
	ds_write_b16 v212, v246 offset:32
	ds_write_b16_d16_hi v212, v246 offset:304
	ds_write_b16 v212, v247 offset:576
	ds_write_b16_d16_hi v212, v247 offset:848
	ds_read_b128 v[216:219], v211 offset:6656
	ds_read_b128 v[220:223], v211 offset:6720
	v_mul_f32_e32 v200, v62, v200
	v_mul_f32_e32 v201, v62, v201
	v_mul_f32_e32 v202, v62, v202
	v_mul_f32_e32 v203, v62, v203
	v_mul_f32_e32 v204, v62, v204
	v_mul_f32_e32 v205, v62, v205
	v_mul_f32_e32 v206, v62, v206
	v_mul_f32_e32 v207, v62, v207
	s_waitcnt lgkmcnt(0)
	v_mfma_f32_16x16x32_bf16 v[240:243], v[216:219], v[32:35], v[240:243]
	v_mfma_f32_16x16x32_bf16 v[200:203], v[216:219], v[40:43], v[200:203]
	v_mfma_f32_16x16x32_bf16 v[204:207], v[216:219], v[48:51], v[204:207]
	v_mfma_f32_16x16x32_bf16 v[240:243], v[220:223], v[36:39], v[240:243]
	v_mfma_f32_16x16x32_bf16 v[200:203], v[220:223], v[44:47], v[200:203]
	v_mfma_f32_16x16x32_bf16 v[204:207], v[220:223], v[52:55], v[204:207]
	s_nop 7
	s_nop 1
	v_cvt_pk_bf16_f32 v244, v240, v241
	v_cvt_pk_bf16_f32 v245, v242, v243
	global_store_dwordx2 v249, v[244:245], s[20:21] offset:32
	v_cvt_pk_bf16_f32 v246, v200, v201
	v_cvt_pk_bf16_f32 v247, v202, v203
	ds_write_b16 v212, v246 offset:6656
	ds_write_b16_d16_hi v212, v246 offset:6928
	ds_write_b16 v212, v247 offset:7200
	ds_write_b16_d16_hi v212, v247 offset:7472
	v_cvt_pk_bf16_f32 v246, v204, v205
	v_cvt_pk_bf16_f32 v247, v206, v207
	ds_write_b16 v212, v246 offset:6688
	ds_write_b16_d16_hi v212, v246 offset:6960
	ds_write_b16 v212, v247 offset:7232
	ds_write_b16_d16_hi v212, v247 offset:7504
	s_add_u32 s20, s20, 0x20000
	s_addc_u32 s21, s21, 0
	s_add_i32 s26, s26, 1
	s_waitcnt lgkmcnt(0)
	s_barrier
	global_load_dwordx4 v[0:3], v213, s[8:9] offset:0
	global_load_dwordx4 v[4:7], v213, s[8:9] offset:64
	global_load_dwordx4 v[8:11], v213, s[8:9] offset:128
	global_load_dwordx4 v[12:15], v213, s[8:9] offset:192
	global_load_dwordx4 v[16:19], v213, s[10:11] offset:0
	global_load_dwordx4 v[20:23], v213, s[10:11] offset:64
	global_load_dwordx4 v[24:27], v213, s[10:11] offset:128
	global_load_dwordx4 v[28:31], v213, s[10:11] offset:192
	global_load_dwordx4 v[32:35], v214, s[14:15] offset:0
	global_load_dwordx4 v[36:39], v214, s[14:15] offset:64
	global_load_dwordx4 v[40:43], v215, s[12:13] offset:0
	global_load_dwordx4 v[44:47], v215, s[12:13] offset:64
	global_load_dwordx4 v[48:51], v215, s[12:13] offset:2048
	global_load_dwordx4 v[52:55], v215, s[12:13] offset:2112
	global_load_dwordx2 v[56:57], v248, s[16:17] offset:0
	global_load_dwordx2 v[58:59], v248, s[16:17] offset:32
	global_load_dword v62, v250, s[18:19]
	s_cmp_lt_u32 s22, 63
	s_cselect_b32 s0, 0x4000, 0
	s_cselect_b32 s23, 0x2000, 0
	s_cselect_b32 s24, 4, 0
	s_add_u32 s8, s8, s0
	s_addc_u32 s9, s9, 0
	s_add_u32 s10, s10, s0
	s_addc_u32 s11, s11, 0
	s_add_u32 s12, s12, s0
	s_addc_u32 s13, s13, 0
	s_add_u32 s16, s16, s0
	s_addc_u32 s17, s17, 0
	s_add_u32 s14, s14, s23
	s_addc_u32 s15, s15, 0
	s_add_u32 s18, s18, s24
	s_addc_u32 s19, s19, 0
	s_add_i32 s22, s22, 1
	s_waitcnt vmcnt(34)
	ds_read_b128 v[216:219], v209 offset:0
	ds_read_b128 v[220:223], v209 offset:64
	ds_read_b128 v[224:227], v209 offset:128
	ds_read_b128 v[228:231], v209 offset:192
	s_waitcnt lgkmcnt(0)
	v_mfma_f32_16x16x32_bf16 v[232:235], v[216:219], v[64:67], 0
	v_mfma_f32_16x16x32_bf16 v[236:239], v[216:219], v[80:83], 0
	v_mfma_f32_16x16x32_bf16 v[232:235], v[220:223], v[68:71], v[232:235]
	v_mfma_f32_16x16x32_bf16 v[236:239], v[220:223], v[84:87], v[236:239]
	v_mfma_f32_16x16x32_bf16 v[232:235], v[224:227], v[72:75], v[232:235]
	v_mfma_f32_16x16x32_bf16 v[236:239], v[224:227], v[88:91], v[236:239]
	v_mfma_f32_16x16x32_bf16 v[232:235], v[228:231], v[76:79], v[232:235]
	v_mfma_f32_16x16x32_bf16 v[236:239], v[228:231], v[92:95], v[236:239]
	s_nop 7
	s_nop 1
	v_lshlrev_b32_e32 v244, 16, v120
	v_and_b32_e32 v245, 0xffff0000, v120
	v_lshlrev_b32_e32 v246, 16, v121
	v_and_b32_e32 v247, 0xffff0000, v121
	v_sub_f32_e32 v244, v244, v232
	v_sub_f32_e32 v245, v245, v233
	v_sub_f32_e32 v246, v246, v234
	v_sub_f32_e32 v247, v247, v235
	v_cvt_pk_bf16_f32 v244, v244, v245
	v_cvt_pk_bf16_f32 v246, v246, v247
	ds_write_b16 v210, v244 offset:0
	ds_write_b16_d16_hi v210, v244 offset:144
	ds_write_b16 v210, v246 offset:288
	ds_write_b16_d16_hi v210, v246 offset:432
	ds_read_b128 v[216:219], v209 offset:6656
	ds_read_b128 v[220:223], v209 offset:6720
	ds_read_b128 v[224:227], v209 offset:6784
	ds_read_b128 v[228:231], v209 offset:6848
	s_waitcnt lgkmcnt(0)
	v_mfma_f32_16x16x32_bf16 v[232:235], v[216:219], v[64:67], 0
	v_mfma_f32_16x16x32_bf16 v[240:243], v[216:219], v[80:83], 0
	v_mfma_f32_16x16x32_bf16 v[232:235], v[220:223], v[68:71], v[232:235]
	v_mfma_f32_16x16x32_bf16 v[240:243], v[220:223], v[84:87], v[240:243]
	v_mfma_f32_16x16x32_bf16 v[232:235], v[224:227], v[72:75], v[232:235]
	v_mfma_f32_16x16x32_bf16 v[240:243], v[224:227], v[88:91], v[240:243]
	v_mfma_f32_16x16x32_bf16 v[232:235], v[228:231], v[76:79], v[232:235]
	v_mfma_f32_16x16x32_bf16 v[240:243], v[228:231], v[92:95], v[240:243]
	s_nop 7
	s_nop 1
	v_lshlrev_b32_e32 v244, 16, v122
	v_and_b32_e32 v245, 0xffff0000, v122
	v_lshlrev_b32_e32 v246, 16, v123
	v_and_b32_e32 v247, 0xffff0000, v123
	v_sub_f32_e32 v244, v244, v232
	v_sub_f32_e32 v245, v245, v233
	v_sub_f32_e32 v246, v246, v234
	v_sub_f32_e32 v247, v247, v235
	v_cvt_pk_bf16_f32 v244, v244, v245
	v_cvt_pk_bf16_f32 v246, v246, v247
	ds_write_b16 v210, v244 offset:6656
	ds_write_b16_d16_hi v210, v244 offset:6800
	ds_write_b16 v210, v246 offset:6944
	ds_write_b16_d16_hi v210, v246 offset:7088
	s_waitcnt lgkmcnt(0)
	s_barrier
	ds_read_b128 v[216:219], v211 offset:0
	ds_read_b128 v[220:223], v211 offset:64
	v_mul_f32_e32 v192, v126, v192
	v_mul_f32_e32 v193, v126, v193
	v_mul_f32_e32 v194, v126, v194
	v_mul_f32_e32 v195, v126, v195
	v_mul_f32_e32 v196, v126, v196
	v_mul_f32_e32 v197, v126, v197
	v_mul_f32_e32 v198, v126, v198
	v_mul_f32_e32 v199, v126, v199
	s_waitcnt lgkmcnt(0)
	v_mfma_f32_16x16x32_bf16 v[236:239], v[216:219], v[96:99], v[236:239]
	v_mfma_f32_16x16x32_bf16 v[192:195], v[216:219], v[104:107], v[192:195]
	v_mfma_f32_16x16x32_bf16 v[196:199], v[216:219], v[112:115], v[196:199]
	v_mfma_f32_16x16x32_bf16 v[236:239], v[220:223], v[100:103], v[236:239]
	v_mfma_f32_16x16x32_bf16 v[192:195], v[220:223], v[108:111], v[192:195]
	v_mfma_f32_16x16x32_bf16 v[196:199], v[220:223], v[116:119], v[196:199]
	s_nop 7
	s_nop 1
	v_cvt_pk_bf16_f32 v244, v236, v237
	v_cvt_pk_bf16_f32 v245, v238, v239
	global_store_dwordx2 v249, v[244:245], s[20:21] offset:0
	v_cvt_pk_bf16_f32 v246, v192, v193
	v_cvt_pk_bf16_f32 v247, v194, v195
	ds_write_b16 v212, v246 offset:0
	ds_write_b16_d16_hi v212, v246 offset:272
	ds_write_b16 v212, v247 offset:544
	ds_write_b16_d16_hi v212, v247 offset:816
	v_cvt_pk_bf16_f32 v246, v196, v197
	v_cvt_pk_bf16_f32 v247, v198, v199
	ds_write_b16 v212, v246 offset:32
	ds_write_b16_d16_hi v212, v246 offset:304
	ds_write_b16 v212, v247 offset:576
	ds_write_b16_d16_hi v212, v247 offset:848
	ds_read_b128 v[216:219], v211 offset:6656
	ds_read_b128 v[220:223], v211 offset:6720
	v_mul_f32_e32 v200, v126, v200
	v_mul_f32_e32 v201, v126, v201
	v_mul_f32_e32 v202, v126, v202
	v_mul_f32_e32 v203, v126, v203
	v_mul_f32_e32 v204, v126, v204
	v_mul_f32_e32 v205, v126, v205
	v_mul_f32_e32 v206, v126, v206
	v_mul_f32_e32 v207, v126, v207
	s_waitcnt lgkmcnt(0)
	v_mfma_f32_16x16x32_bf16 v[240:243], v[216:219], v[96:99], v[240:243]
	v_mfma_f32_16x16x32_bf16 v[200:203], v[216:219], v[104:107], v[200:203]
	v_mfma_f32_16x16x32_bf16 v[204:207], v[216:219], v[112:115], v[204:207]
	v_mfma_f32_16x16x32_bf16 v[240:243], v[220:223], v[100:103], v[240:243]
	v_mfma_f32_16x16x32_bf16 v[200:203], v[220:223], v[108:111], v[200:203]
	v_mfma_f32_16x16x32_bf16 v[204:207], v[220:223], v[116:119], v[204:207]
	s_nop 7
	s_nop 1
	v_cvt_pk_bf16_f32 v244, v240, v241
	v_cvt_pk_bf16_f32 v245, v242, v243
	global_store_dwordx2 v249, v[244:245], s[20:21] offset:32
	v_cvt_pk_bf16_f32 v246, v200, v201
	v_cvt_pk_bf16_f32 v247, v202, v203
	ds_write_b16 v212, v246 offset:6656
	ds_write_b16_d16_hi v212, v246 offset:6928
	ds_write_b16 v212, v247 offset:7200
	ds_write_b16_d16_hi v212, v247 offset:7472
	v_cvt_pk_bf16_f32 v246, v204, v205
	v_cvt_pk_bf16_f32 v247, v206, v207
	ds_write_b16 v212, v246 offset:6688
	ds_write_b16_d16_hi v212, v246 offset:6960
	ds_write_b16 v212, v247 offset:7232
	ds_write_b16_d16_hi v212, v247 offset:7504
	s_add_u32 s20, s20, 0x20000
	s_addc_u32 s21, s21, 0
	s_add_i32 s26, s26, 1
	s_waitcnt lgkmcnt(0)
	s_barrier
	global_load_dwordx4 v[64:67], v213, s[8:9] offset:0
	global_load_dwordx4 v[68:71], v213, s[8:9] offset:64
	global_load_dwordx4 v[72:75], v213, s[8:9] offset:128
	global_load_dwordx4 v[76:79], v213, s[8:9] offset:192
	global_load_dwordx4 v[80:83], v213, s[10:11] offset:0
	global_load_dwordx4 v[84:87], v213, s[10:11] offset:64
	global_load_dwordx4 v[88:91], v213, s[10:11] offset:128
	global_load_dwordx4 v[92:95], v213, s[10:11] offset:192
	global_load_dwordx4 v[96:99], v214, s[14:15] offset:0
	global_load_dwordx4 v[100:103], v214, s[14:15] offset:64
	global_load_dwordx4 v[104:107], v215, s[12:13] offset:0
	global_load_dwordx4 v[108:111], v215, s[12:13] offset:64
	global_load_dwordx4 v[112:115], v215, s[12:13] offset:2048
	global_load_dwordx4 v[116:119], v215, s[12:13] offset:2112
	global_load_dwordx2 v[120:121], v248, s[16:17] offset:0
	global_load_dwordx2 v[122:123], v248, s[16:17] offset:32
	global_load_dword v126, v250, s[18:19]
	s_cmp_lt_u32 s22, 63
	s_cselect_b32 s0, 0x4000, 0
	s_cselect_b32 s23, 0x2000, 0
	s_cselect_b32 s24, 4, 0
	s_add_u32 s8, s8, s0
	s_addc_u32 s9, s9, 0
	s_add_u32 s10, s10, s0
	s_addc_u32 s11, s11, 0
	s_add_u32 s12, s12, s0
	s_addc_u32 s13, s13, 0
	s_add_u32 s16, s16, s0
	s_addc_u32 s17, s17, 0
	s_add_u32 s14, s14, s23
	s_addc_u32 s15, s15, 0
	s_add_u32 s18, s18, s24
	s_addc_u32 s19, s19, 0
	s_add_i32 s22, s22, 1
	s_waitcnt vmcnt(34)
	ds_read_b128 v[216:219], v209 offset:0
	ds_read_b128 v[220:223], v209 offset:64
	ds_read_b128 v[224:227], v209 offset:128
	ds_read_b128 v[228:231], v209 offset:192
	s_waitcnt lgkmcnt(0)
	v_mfma_f32_16x16x32_bf16 v[232:235], v[216:219], v[128:131], 0
	v_mfma_f32_16x16x32_bf16 v[236:239], v[216:219], v[144:147], 0
	v_mfma_f32_16x16x32_bf16 v[232:235], v[220:223], v[132:135], v[232:235]
	v_mfma_f32_16x16x32_bf16 v[236:239], v[220:223], v[148:151], v[236:239]
	v_mfma_f32_16x16x32_bf16 v[232:235], v[224:227], v[136:139], v[232:235]
	v_mfma_f32_16x16x32_bf16 v[236:239], v[224:227], v[152:155], v[236:239]
	v_mfma_f32_16x16x32_bf16 v[232:235], v[228:231], v[140:143], v[232:235]
	v_mfma_f32_16x16x32_bf16 v[236:239], v[228:231], v[156:159], v[236:239]
	s_nop 7
	s_nop 1
	v_lshlrev_b32_e32 v244, 16, v184
	v_and_b32_e32 v245, 0xffff0000, v184
	v_lshlrev_b32_e32 v246, 16, v185
	v_and_b32_e32 v247, 0xffff0000, v185
	v_sub_f32_e32 v244, v244, v232
	v_sub_f32_e32 v245, v245, v233
	v_sub_f32_e32 v246, v246, v234
	v_sub_f32_e32 v247, v247, v235
	v_cvt_pk_bf16_f32 v244, v244, v245
	v_cvt_pk_bf16_f32 v246, v246, v247
	ds_write_b16 v210, v244 offset:0
	ds_write_b16_d16_hi v210, v244 offset:144
	ds_write_b16 v210, v246 offset:288
	ds_write_b16_d16_hi v210, v246 offset:432
	ds_read_b128 v[216:219], v209 offset:6656
	ds_read_b128 v[220:223], v209 offset:6720
	ds_read_b128 v[224:227], v209 offset:6784
	ds_read_b128 v[228:231], v209 offset:6848
	s_waitcnt lgkmcnt(0)
	v_mfma_f32_16x16x32_bf16 v[232:235], v[216:219], v[128:131], 0
	v_mfma_f32_16x16x32_bf16 v[240:243], v[216:219], v[144:147], 0
	v_mfma_f32_16x16x32_bf16 v[232:235], v[220:223], v[132:135], v[232:235]
	v_mfma_f32_16x16x32_bf16 v[240:243], v[220:223], v[148:151], v[240:243]
	v_mfma_f32_16x16x32_bf16 v[232:235], v[224:227], v[136:139], v[232:235]
	v_mfma_f32_16x16x32_bf16 v[240:243], v[224:227], v[152:155], v[240:243]
	v_mfma_f32_16x16x32_bf16 v[232:235], v[228:231], v[140:143], v[232:235]
	v_mfma_f32_16x16x32_bf16 v[240:243], v[228:231], v[156:159], v[240:243]
	s_nop 7
	s_nop 1
	v_lshlrev_b32_e32 v244, 16, v186
	v_and_b32_e32 v245, 0xffff0000, v186
	v_lshlrev_b32_e32 v246, 16, v187
	v_and_b32_e32 v247, 0xffff0000, v187
	v_sub_f32_e32 v244, v244, v232
	v_sub_f32_e32 v245, v245, v233
	v_sub_f32_e32 v246, v246, v234
	v_sub_f32_e32 v247, v247, v235
	v_cvt_pk_bf16_f32 v244, v244, v245
	v_cvt_pk_bf16_f32 v246, v246, v247
	ds_write_b16 v210, v244 offset:6656
	ds_write_b16_d16_hi v210, v244 offset:6800
	ds_write_b16 v210, v246 offset:6944
	ds_write_b16_d16_hi v210, v246 offset:7088
	s_waitcnt lgkmcnt(0)
	s_barrier
	ds_read_b128 v[216:219], v211 offset:0
	ds_read_b128 v[220:223], v211 offset:64
	v_mul_f32_e32 v192, v190, v192
	v_mul_f32_e32 v193, v190, v193
	v_mul_f32_e32 v194, v190, v194
	v_mul_f32_e32 v195, v190, v195
	v_mul_f32_e32 v196, v190, v196
	v_mul_f32_e32 v197, v190, v197
	v_mul_f32_e32 v198, v190, v198
	v_mul_f32_e32 v199, v190, v199
	s_waitcnt lgkmcnt(0)
	v_mfma_f32_16x16x32_bf16 v[236:239], v[216:219], v[160:163], v[236:239]
	v_mfma_f32_16x16x32_bf16 v[192:195], v[216:219], v[168:171], v[192:195]
	v_mfma_f32_16x16x32_bf16 v[196:199], v[216:219], v[176:179], v[196:199]
	v_mfma_f32_16x16x32_bf16 v[236:239], v[220:223], v[164:167], v[236:239]
	v_mfma_f32_16x16x32_bf16 v[192:195], v[220:223], v[172:175], v[192:195]
	v_mfma_f32_16x16x32_bf16 v[196:199], v[220:223], v[180:183], v[196:199]
	s_nop 7
	s_nop 1
	v_cvt_pk_bf16_f32 v244, v236, v237
	v_cvt_pk_bf16_f32 v245, v238, v239
	global_store_dwordx2 v249, v[244:245], s[20:21] offset:0
	v_cvt_pk_bf16_f32 v246, v192, v193
	v_cvt_pk_bf16_f32 v247, v194, v195
	ds_write_b16 v212, v246 offset:0
	ds_write_b16_d16_hi v212, v246 offset:272
	ds_write_b16 v212, v247 offset:544
	ds_write_b16_d16_hi v212, v247 offset:816
	v_cvt_pk_bf16_f32 v246, v196, v197
	v_cvt_pk_bf16_f32 v247, v198, v199
	ds_write_b16 v212, v246 offset:32
	ds_write_b16_d16_hi v212, v246 offset:304
	ds_write_b16 v212, v247 offset:576
	ds_write_b16_d16_hi v212, v247 offset:848
	ds_read_b128 v[216:219], v211 offset:6656
	ds_read_b128 v[220:223], v211 offset:6720
	v_mul_f32_e32 v200, v190, v200
	v_mul_f32_e32 v201, v190, v201
	v_mul_f32_e32 v202, v190, v202
	v_mul_f32_e32 v203, v190, v203
	v_mul_f32_e32 v204, v190, v204
	v_mul_f32_e32 v205, v190, v205
	v_mul_f32_e32 v206, v190, v206
	v_mul_f32_e32 v207, v190, v207
	s_waitcnt lgkmcnt(0)
	v_mfma_f32_16x16x32_bf16 v[240:243], v[216:219], v[160:163], v[240:243]
	v_mfma_f32_16x16x32_bf16 v[200:203], v[216:219], v[168:171], v[200:203]
	v_mfma_f32_16x16x32_bf16 v[204:207], v[216:219], v[176:179], v[204:207]
	v_mfma_f32_16x16x32_bf16 v[240:243], v[220:223], v[164:167], v[240:243]
	v_mfma_f32_16x16x32_bf16 v[200:203], v[220:223], v[172:175], v[200:203]
	v_mfma_f32_16x16x32_bf16 v[204:207], v[220:223], v[180:183], v[204:207]
	s_nop 7
	s_nop 1
	v_cvt_pk_bf16_f32 v244, v240, v241
	v_cvt_pk_bf16_f32 v245, v242, v243
	global_store_dwordx2 v249, v[244:245], s[20:21] offset:32
	v_cvt_pk_bf16_f32 v246, v200, v201
	v_cvt_pk_bf16_f32 v247, v202, v203
	ds_write_b16 v212, v246 offset:6656
	ds_write_b16_d16_hi v212, v246 offset:6928
	ds_write_b16 v212, v247 offset:7200
	ds_write_b16_d16_hi v212, v247 offset:7472
	v_cvt_pk_bf16_f32 v246, v204, v205
	v_cvt_pk_bf16_f32 v247, v206, v207
	ds_write_b16 v212, v246 offset:6688
	ds_write_b16_d16_hi v212, v246 offset:6960
	ds_write_b16 v212, v247 offset:7232
	ds_write_b16_d16_hi v212, v247 offset:7504
	s_add_u32 s20, s20, 0x20000
	s_addc_u32 s21, s21, 0
	s_add_i32 s26, s26, 1
	s_waitcnt lgkmcnt(0)
	s_barrier
	s_cmp_lt_u32 s26, 63
	s_cbranch_scc1 .Lsc_loop
	global_load_dwordx4 v[128:131], v213, s[8:9] offset:0
	global_load_dwordx4 v[132:135], v213, s[8:9] offset:64
	global_load_dwordx4 v[136:139], v213, s[8:9] offset:128
	global_load_dwordx4 v[140:143], v213, s[8:9] offset:192
	global_load_dwordx4 v[144:147], v213, s[10:11] offset:0
	global_load_dwordx4 v[148:151], v213, s[10:11] offset:64
	global_load_dwordx4 v[152:155], v213, s[10:11] offset:128
	global_load_dwordx4 v[156:159], v213, s[10:11] offset:192
	global_load_dwordx4 v[160:163], v214, s[14:15] offset:0
	global_load_dwordx4 v[164:167], v214, s[14:15] offset:64
	global_load_dwordx4 v[168:171], v215, s[12:13] offset:0
	global_load_dwordx4 v[172:175], v215, s[12:13] offset:64
	global_load_dwordx4 v[176:179], v215, s[12:13] offset:2048
	global_load_dwordx4 v[180:183], v215, s[12:13] offset:2112
	global_load_dwordx2 v[184:185], v248, s[16:17] offset:0
	global_load_dwordx2 v[186:187], v248, s[16:17] offset:32
	global_load_dword v190, v250, s[18:19]
	s_cmp_lt_u32 s22, 63
	s_cselect_b32 s0, 0x4000, 0
	s_cselect_b32 s23, 0x2000, 0
	s_cselect_b32 s24, 4, 0
	s_add_u32 s8, s8, s0
	s_addc_u32 s9, s9, 0
	s_add_u32 s10, s10, s0
	s_addc_u32 s11, s11, 0
	s_add_u32 s12, s12, s0
	s_addc_u32 s13, s13, 0
	s_add_u32 s16, s16, s0
	s_addc_u32 s17, s17, 0
	s_add_u32 s14, s14, s23
	s_addc_u32 s15, s15, 0
	s_add_u32 s18, s18, s24
	s_addc_u32 s19, s19, 0
	s_add_i32 s22, s22, 1
	s_waitcnt vmcnt(34)
	ds_read_b128 v[216:219], v209 offset:0
	ds_read_b128 v[220:223], v209 offset:64
	ds_read_b128 v[224:227], v209 offset:128
	ds_read_b128 v[228:231], v209 offset:192
	s_waitcnt lgkmcnt(0)
	v_mfma_f32_16x16x32_bf16 v[232:235], v[216:219], v[0:3], 0
	v_mfma_f32_16x16x32_bf16 v[236:239], v[216:219], v[16:19], 0
	v_mfma_f32_16x16x32_bf16 v[232:235], v[220:223], v[4:7], v[232:235]
	v_mfma_f32_16x16x32_bf16 v[236:239], v[220:223], v[20:23], v[236:239]
	v_mfma_f32_16x16x32_bf16 v[232:235], v[224:227], v[8:11], v[232:235]
	v_mfma_f32_16x16x32_bf16 v[236:239], v[224:227], v[24:27], v[236:239]
	v_mfma_f32_16x16x32_bf16 v[232:235], v[228:231], v[12:15], v[232:235]
	v_mfma_f32_16x16x32_bf16 v[236:239], v[228:231], v[28:31], v[236:239]
	s_nop 7
	s_nop 1
	v_lshlrev_b32_e32 v244, 16, v56
	v_and_b32_e32 v245, 0xffff0000, v56
	v_lshlrev_b32_e32 v246, 16, v57
	v_and_b32_e32 v247, 0xffff0000, v57
	v_sub_f32_e32 v244, v244, v232
	v_sub_f32_e32 v245, v245, v233
	v_sub_f32_e32 v246, v246, v234
	v_sub_f32_e32 v247, v247, v235
	v_cvt_pk_bf16_f32 v244, v244, v245
	v_cvt_pk_bf16_f32 v246, v246, v247
	ds_write_b16 v210, v244 offset:0
	ds_write_b16_d16_hi v210, v244 offset:144
	ds_write_b16 v210, v246 offset:288
	ds_write_b16_d16_hi v210, v246 offset:432
	ds_read_b128 v[216:219], v209 offset:6656
	ds_read_b128 v[220:223], v209 offset:6720
	ds_read_b128 v[224:227], v209 offset:6784
	ds_read_b128 v[228:231], v209 offset:6848
	s_waitcnt lgkmcnt(0)
	v_mfma_f32_16x16x32_bf16 v[232:235], v[216:219], v[0:3], 0
	v_mfma_f32_16x16x32_bf16 v[240:243], v[216:219], v[16:19], 0
	v_mfma_f32_16x16x32_bf16 v[232:235], v[220:223], v[4:7], v[232:235]
	v_mfma_f32_16x16x32_bf16 v[240:243], v[220:223], v[20:23], v[240:243]
	v_mfma_f32_16x16x32_bf16 v[232:235], v[224:227], v[8:11], v[232:235]
	v_mfma_f32_16x16x32_bf16 v[240:243], v[224:227], v[24:27], v[240:243]
	v_mfma_f32_16x16x32_bf16 v[232:235], v[228:231], v[12:15], v[232:235]
	v_mfma_f32_16x16x32_bf16 v[240:243], v[228:231], v[28:31], v[240:243]
	s_nop 7
	s_nop 1
	v_lshlrev_b32_e32 v244, 16, v58
	v_and_b32_e32 v245, 0xffff0000, v58
	v_lshlrev_b32_e32 v246, 16, v59
	v_and_b32_e32 v247, 0xffff0000, v59
	v_sub_f32_e32 v244, v244, v232
	v_sub_f32_e32 v245, v245, v233
	v_sub_f32_e32 v246, v246, v234
	v_sub_f32_e32 v247, v247, v235
	v_cvt_pk_bf16_f32 v244, v244, v245
	v_cvt_pk_bf16_f32 v246, v246, v247
	ds_write_b16 v210, v244 offset:6656
	ds_write_b16_d16_hi v210, v244 offset:6800
	ds_write_b16 v210, v246 offset:6944
	ds_write_b16_d16_hi v210, v246 offset:7088
	s_waitcnt lgkmcnt(0)
	s_barrier
	ds_read_b128 v[216:219], v211 offset:0
	ds_read_b128 v[220:223], v211 offset:64
	v_mul_f32_e32 v192, v62, v192
	v_mul_f32_e32 v193, v62, v193
	v_mul_f32_e32 v194, v62, v194
	v_mul_f32_e32 v195, v62, v195
	v_mul_f32_e32 v196, v62, v196
	v_mul_f32_e32 v197, v62, v197
	v_mul_f32_e32 v198, v62, v198
	v_mul_f32_e32 v199, v62, v199
	s_waitcnt lgkmcnt(0)
	v_mfma_f32_16x16x32_bf16 v[236:239], v[216:219], v[32:35], v[236:239]
	v_mfma_f32_16x16x32_bf16 v[192:195], v[216:219], v[40:43], v[192:195]
	v_mfma_f32_16x16x32_bf16 v[196:199], v[216:219], v[48:51], v[196:199]
	v_mfma_f32_16x16x32_bf16 v[236:239], v[220:223], v[36:39], v[236:239]
	v_mfma_f32_16x16x32_bf16 v[192:195], v[220:223], v[44:47], v[192:195]
	v_mfma_f32_16x16x32_bf16 v[196:199], v[220:223], v[52:55], v[196:199]
	s_nop 7
	s_nop 1
	v_cvt_pk_bf16_f32 v244, v236, v237
	v_cvt_pk_bf16_f32 v245, v238, v239
	global_store_dwordx2 v249, v[244:245], s[20:21] offset:0
	v_cvt_pk_bf16_f32 v246, v192, v193
	v_cvt_pk_bf16_f32 v247, v194, v195
	ds_write_b16 v212, v246 offset:0
	ds_write_b16_d16_hi v212, v246 offset:272
	ds_write_b16 v212, v247 offset:544
	ds_write_b16_d16_hi v212, v247 offset:816
	v_cvt_pk_bf16_f32 v246, v196, v197
	v_cvt_pk_bf16_f32 v247, v198, v199
	ds_write_b16 v212, v246 offset:32
	ds_write_b16_d16_hi v212, v246 offset:304
	ds_write_b16 v212, v247 offset:576
	ds_write_b16_d16_hi v212, v247 offset:848
	ds_read_b128 v[216:219], v211 offset:6656
	ds_read_b128 v[220:223], v211 offset:6720
	v_mul_f32_e32 v200, v62, v200
	v_mul_f32_e32 v201, v62, v201
	v_mul_f32_e32 v202, v62, v202
	v_mul_f32_e32 v203, v62, v203
	v_mul_f32_e32 v204, v62, v204
	v_mul_f32_e32 v205, v62, v205
	v_mul_f32_e32 v206, v62, v206
	v_mul_f32_e32 v207, v62, v207
	s_waitcnt lgkmcnt(0)
	v_mfma_f32_16x16x32_bf16 v[240:243], v[216:219], v[32:35], v[240:243]
	v_mfma_f32_16x16x32_bf16 v[200:203], v[216:219], v[40:43], v[200:203]
	v_mfma_f32_16x16x32_bf16 v[204:207], v[216:219], v[48:51], v[204:207]
	v_mfma_f32_16x16x32_bf16 v[240:243], v[220:223], v[36:39], v[240:243]
	v_mfma_f32_16x16x32_bf16 v[200:203], v[220:223], v[44:47], v[200:203]
	v_mfma_f32_16x16x32_bf16 v[204:207], v[220:223], v[52:55], v[204:207]
	s_nop 7
	s_nop 1
	v_cvt_pk_bf16_f32 v244, v240, v241
	v_cvt_pk_bf16_f32 v245, v242, v243
	global_store_dwordx2 v249, v[244:245], s[20:21] offset:32
	v_cvt_pk_bf16_f32 v246, v200, v201
	v_cvt_pk_bf16_f32 v247, v202, v203
	ds_write_b16 v212, v246 offset:6656
	ds_write_b16_d16_hi v212, v246 offset:6928
	ds_write_b16 v212, v247 offset:7200
	ds_write_b16_d16_hi v212, v247 offset:7472
	v_cvt_pk_bf16_f32 v246, v204, v205
	v_cvt_pk_bf16_f32 v247, v206, v207
	ds_write_b16 v212, v246 offset:6688
	ds_write_b16_d16_hi v212, v246 offset:6960
	ds_write_b16 v212, v247 offset:7232
	ds_write_b16_d16_hi v212, v247 offset:7504
	s_add_u32 s20, s20, 0x20000
	s_addc_u32 s21, s21, 0
	s_add_i32 s26, s26, 1
	s_waitcnt lgkmcnt(0)
	s_barrier
	s_waitcnt vmcnt(0)

